# grid barrier: XCD-leader path also issues its L1 invalidate early (overlapping the arrival atomic) on top of v7
# speedup vs baseline: 1.0145x; 1.0079x over previous
.LBB0_109:
	s_andn2_saveexec_b64 s[2:3], s[8:9]
	s_cbranch_execz .LBB0_129
	s_mov_b64 s[8:9], exec
	buffer_wbl2 sc1
	s_waitcnt lgkmcnt(0)
	s_waitcnt vmcnt(0)
	buffer_inv sc1
	v_mbcnt_lo_u32_b32 v1, s8, 0
	v_mbcnt_hi_u32_b32 v1, s9, v1
	v_cmp_eq_u32_e32 vcc, 0, v1
	s_and_saveexec_b64 s[12:13], vcc
	s_cbranch_execz .LBB0_112
	s_bcnt1_i32_b64 s1, s[8:9]
	v_mov_b32_e32 v2, 0x1ce03000
	v_mov_b32_e32 v3, s1
	global_atomic_add v2, v2, v3, s[10:11] offset:1024 sc0

.LBB0_126:
	s_or_b64 exec, exec, s[8:9]
	s_mov_b64 s[8:9], exec
	v_mbcnt_lo_u32_b32 v0, s8, 0
	v_mbcnt_hi_u32_b32 v0, s9, v0
	s_mov_b32 s15, 0
	v_cmp_eq_u32_e32 vcc, 0, v0
	s_waitcnt vmcnt(0)
	s_and_saveexec_b64 s[12:13], vcc
	s_cbranch_execz .LBB0_128
	s_add_i32 s14, s0, 0x900
	s_lshl_b64 s[0:1], s[14:15], 2
	s_add_u32 s0, s92, s0
	s_addc_u32 s1, s93, s1
	s_bcnt1_i32_b64 s2, s[8:9]
	v_mov_b32_e32 v0, 0
	v_mov_b32_e32 v1, s2
	global_atomic_add v0, v1, s[0:1]

.LBB0_395:
	s_andn2_saveexec_b64 s[8:9], s[8:9]
	s_cbranch_execz .LBB0_415
	s_mov_b64 s[10:11], exec
	buffer_wbl2 sc1
	s_waitcnt lgkmcnt(0)
	s_waitcnt vmcnt(0)
	buffer_inv sc1
	v_mbcnt_lo_u32_b32 v1, s10, 0
	v_mbcnt_hi_u32_b32 v1, s11, v1
	v_cmp_eq_u32_e32 vcc, 0, v1
	s_and_saveexec_b64 s[12:13], vcc
	s_cbranch_execz .LBB0_398
	s_bcnt1_i32_b64 s10, s[10:11]
	v_mov_b32_e32 v3, s10
	v_readlane_b32 s10, v254, 5
	v_readlane_b32 s11, v254, 6
	s_nop 4
	global_atomic_add v3, v2, v3, s[10:11] sc0

.LBB0_412:
	s_or_b64 exec, exec, s[10:11]
	s_mov_b64 s[10:11], exec
	v_mbcnt_lo_u32_b32 v0, s10, 0
	v_mbcnt_hi_u32_b32 v0, s11, v0
	v_cmp_eq_u32_e32 vcc, 0, v0
	s_waitcnt vmcnt(0)
	s_and_saveexec_b64 s[12:13], vcc
	s_cbranch_execz .LBB0_414
	s_add_i32 s94, s24, 0x900
	s_lshl_b64 s[14:15], s[94:95], 2
	s_add_u32 s14, s92, s14
	s_addc_u32 s15, s93, s15
	s_bcnt1_i32_b64 s10, s[10:11]
	v_mov_b32_e32 v0, s10
	global_atomic_add v2, v0, s[14:15]
	v_readlane_b32 s94, v253, 3
	v_readlane_b32 s87, v254, 62

.LBB0_645:
	s_andn2_saveexec_b64 s[10:11], s[10:11]
	s_cbranch_execz .LBB0_665
	s_mov_b64 s[10:11], exec
	buffer_wbl2 sc1
	s_waitcnt lgkmcnt(0)
	s_waitcnt vmcnt(0)
	buffer_inv sc1
	v_mbcnt_lo_u32_b32 v1, s10, 0
	v_mbcnt_hi_u32_b32 v1, s11, v1
	v_cmp_eq_u32_e32 vcc, 0, v1
	s_and_saveexec_b64 s[12:13], vcc
	s_cbranch_execz .LBB0_648
	s_bcnt1_i32_b64 s7, s[10:11]
	v_readlane_b32 s10, v254, 5
	v_mov_b32_e32 v3, s7
	v_readlane_b32 s11, v254, 6
	s_nop 4
	global_atomic_add v3, v2, v3, s[10:11] sc0

.LBB0_662:
	s_or_b64 exec, exec, s[10:11]
	s_mov_b64 s[10:11], exec
	v_mbcnt_lo_u32_b32 v0, s10, 0
	v_mbcnt_hi_u32_b32 v0, s11, v0
	v_cmp_eq_u32_e32 vcc, 0, v0
	s_waitcnt vmcnt(0)
	s_and_saveexec_b64 s[12:13], vcc
	s_cbranch_execz .LBB0_664
	s_add_i32 s94, s6, 0x900
	s_lshl_b64 s[6:7], s[94:95], 2
	s_add_u32 s6, s92, s6
	s_addc_u32 s7, s93, s7
	s_bcnt1_i32_b64 s10, s[10:11]
	v_mov_b32_e32 v0, s10
	global_atomic_add v2, v0, s[6:7]
	v_readlane_b32 s94, v253, 3
	v_readlane_b32 s87, v254, 62

.LBB0_773:
	s_andn2_saveexec_b64 s[10:11], s[10:11]
	s_cbranch_execz .LBB0_793
	s_mov_b64 s[12:13], exec
	buffer_wbl2 sc1
	s_waitcnt lgkmcnt(0)
	s_waitcnt vmcnt(0)
	buffer_inv sc1
	v_mbcnt_lo_u32_b32 v1, s12, 0
	v_mbcnt_hi_u32_b32 v1, s13, v1
	v_cmp_eq_u32_e32 vcc, 0, v1
	s_and_saveexec_b64 s[14:15], vcc
	s_cbranch_execz .LBB0_776
	s_bcnt1_i32_b64 s7, s[12:13]
	v_readlane_b32 s12, v254, 5
	v_mov_b32_e32 v3, s7
	v_readlane_b32 s13, v254, 6
	s_nop 4
	global_atomic_add v3, v2, v3, s[12:13] sc0

.LBB0_790:
	s_or_b64 exec, exec, s[12:13]
	s_mov_b64 s[12:13], exec
	v_mbcnt_lo_u32_b32 v0, s12, 0
	v_mbcnt_hi_u32_b32 v0, s13, v0
	v_cmp_eq_u32_e32 vcc, 0, v0
	s_waitcnt vmcnt(0)
	s_and_saveexec_b64 s[14:15], vcc
	s_cbranch_execz .LBB0_792
	s_add_i32 s94, s6, 0x900
	s_lshl_b64 s[6:7], s[94:95], 2
	s_add_u32 s6, s92, s6
	s_addc_u32 s7, s93, s7
	s_bcnt1_i32_b64 s12, s[12:13]
	v_mov_b32_e32 v0, s12
	global_atomic_add v2, v0, s[6:7]
	v_readlane_b32 s94, v253, 3
	v_readlane_b32 s87, v254, 62

.LBB0_890:
	s_andn2_saveexec_b64 s[8:9], s[8:9]
	s_cbranch_execz .LBB0_131
	s_mov_b64 s[8:9], exec
	buffer_wbl2 sc1
	s_waitcnt lgkmcnt(0)
	s_waitcnt vmcnt(0)
	buffer_inv sc1
	v_mbcnt_lo_u32_b32 v1, s8, 0
	v_mbcnt_hi_u32_b32 v1, s9, v1
	v_cmp_eq_u32_e32 vcc, 0, v1
	s_and_saveexec_b64 s[10:11], vcc
	s_cbranch_execz .LBB0_893
	s_bcnt1_i32_b64 s8, s[8:9]
	v_mov_b32_e32 v3, s8
	v_readlane_b32 s8, v254, 5
	v_readlane_b32 s9, v254, 6
	s_nop 4
	global_atomic_add v3, v2, v3, s[8:9] sc0

.LBB0_907:
	s_or_b64 exec, exec, s[8:9]
	s_mov_b64 s[8:9], exec
	v_mbcnt_lo_u32_b32 v0, s8, 0
	v_mbcnt_hi_u32_b32 v0, s9, v0
	v_cmp_eq_u32_e32 vcc, 0, v0
	s_waitcnt vmcnt(0)
	s_and_saveexec_b64 s[10:11], vcc
	s_cbranch_execz .LBB0_130
	s_add_i32 s94, s24, 0x900
	s_lshl_b64 s[12:13], s[94:95], 2
	s_add_u32 s12, s92, s12
	s_addc_u32 s13, s93, s13
	s_bcnt1_i32_b64 s8, s[8:9]
	v_mov_b32_e32 v0, s8
	global_atomic_add v2, v0, s[12:13]
	v_readlane_b32 s94, v253, 3
	v_readlane_b32 s87, v254, 62
	s_branch .LBB0_130
